# scan loop: six-slot ring + next-step operand prefetch (LDS reads under MFMAs)
# baseline (speedup 1.0000x reference)
.LBB0_1501:
	s_cmpk_gt_u32 s57, 0xbf
	s_cselect_b64 s[22:23], -1, 0
	s_and_b32 s8, s90, 56
	s_cmp_lg_u32 s8, 0
	s_cselect_b64 s[10:11], -1, 0
	s_bitcmp1_b32 s90, 6
	v_cndmask_b32_e64 v42, 0, 1, s[10:11]
	s_cselect_b64 s[24:25], -1, 0
	v_cmp_eq_u32_e64 s[8:9], 0, v50
	v_add_u32_e32 v160, v160, v158
	s_mov_b32 s35, 5
	s_movk_i32 s36, 0xfe
	v_cmp_ne_u32_e64 s[10:11], 1, v42
	s_movk_i32 s37, 0x1800
	v_mov_b32_e32 v182, 0x27020
	ds_read_b64 v[184:185], v182
	v_add_u32_e32 v177, v157, v167
	ds_read_b128 v[134:137], v177
	v_add_u32_e32 v178, v157, v166
	ds_read_b128 v[138:141], v177 offset:4096
	ds_read_b128 v[126:129], v178
	v_add_u32_e32 v177, v157, v168
	ds_read_b128 v[130:133], v178 offset:4096
	ds_read_b128 v[118:121], v177
	v_add_u32_e32 v176, v157, v169
	ds_read_b128 v[122:125], v177 offset:4096
	ds_read_b128 v[114:117], v176
	ds_read_b128 v[110:113], v176 offset:4096
	s_and_b64 vcc, exec, s[12:13]
	s_cbranch_vccnz .Lsc_pre_noa
	ds_read_b128 v[2:5], v160 offset:24576
	ds_read_b128 v[6:9], v160 offset:25600
.Lsc_pre_noa:
	ds_read_b128 v[42:45], v159 offset:16384
	s_waitcnt lgkmcnt(0)
	s_branch .LBB0_1504
.LBB0_1504:
	s_and_b64 vcc, exec, s[22:23]
	s_cbranch_vccz .Lsc_wlo
	s_waitcnt vmcnt(15)
	s_branch .Lsc_wdone
.Lsc_wlo:
	s_waitcnt vmcnt(18)

.Lsc_pre_cn:
	s_mov_b32 s29, 4
	s_add_i32 s26, s28, s31
	s_mulk_i32 s29, 0x6a00
	s_ashr_i32 s27, s26, 31
	s_add_i32 s38, s29, 0
	s_lshl_b64 s[40:41], s[26:27], 14
	s_add_i32 s29, s38, s30
	v_lshl_add_u64 v[180:181], v[142:143], 0, s[40:41]
	s_mov_b32 m0, s29
	s_and_b64 vcc, exec, s[0:1]
	global_load_lds_dwordx4 v[180:181], off
	v_lshl_add_u64 v[180:181], v[144:145], 0, s[40:41]
	s_add_i32 s40, s28, s34
	s_ashr_i32 s41, s40, 31
	s_add_i32 m0, s29, 0x2000
	s_lshl_b64 s[40:41], s[40:41], 15
	global_load_lds_dwordx4 v[180:181], off
	v_lshl_add_u64 v[180:181], v[146:147], 0, s[40:41]
	s_add_i32 m0, s29, 0x4000
	s_nop 0
	global_load_lds_dwordx4 v[180:181], off
	s_cbranch_vccnz .Lsc_pre_a
	s_lshl_b64 s[40:41], s[26:27], 11
	v_lshl_add_u64 v[180:181], v[148:149], 0, s[40:41]
	s_add_i32 m0, s29, 0x6000
	s_nop 0
	global_load_lds_dwordx4 v[180:181], off

.Lsc_cn_done:
	s_and_b32 s38, s35, 0xffff
	s_mul_i32 s38, s38, 0xaaab
	s_lshr_b32 s38, s38, 18
	s_mul_i32 s38, s38, 6
	s_sub_i32 s29, s35, s38
	s_add_i32 s26, s28, s31
	s_mulk_i32 s29, 0x6a00
	s_ashr_i32 s27, s26, 31
	s_add_i32 s38, s29, 0
	s_lshl_b64 s[40:41], s[26:27], 14
	s_add_i32 s29, s38, s30
	v_lshl_add_u64 v[180:181], v[142:143], 0, s[40:41]
	s_mov_b32 m0, s29
	s_and_b64 vcc, exec, s[0:1]
	global_load_lds_dwordx4 v[180:181], off
	v_lshl_add_u64 v[180:181], v[144:145], 0, s[40:41]
	s_add_i32 s40, s28, s34
	s_ashr_i32 s41, s40, 31
	s_add_i32 m0, s29, 0x2000
	s_lshl_b64 s[40:41], s[40:41], 15
	global_load_lds_dwordx4 v[180:181], off
	v_lshl_add_u64 v[180:181], v[146:147], 0, s[40:41]
	s_add_i32 m0, s29, 0x4000
	s_nop 0
	global_load_lds_dwordx4 v[180:181], off
	s_cbranch_vccnz .LBB0_1525
	s_lshl_b64 s[40:41], s[26:27], 11
	v_lshl_add_u64 v[180:181], v[148:149], 0, s[40:41]
	s_add_i32 m0, s29, 0x6000
	s_nop 0
	global_load_lds_dwordx4 v[180:181], off

.LBB0_1527:
	s_or_b64 exec, exec, s[28:29]
	s_waitcnt lgkmcnt(0)
	s_add_i32 s27, s35, 1
	s_and_b32 s26, 0xffff, s27
	s_mul_i32 s26, s26, 0xaaab
	s_lshr_b32 s26, s26, 18
	s_mul_i32 s26, s26, 6
	s_sub_i32 s26, s27, s26
	s_mulk_i32 s26, 0x6a00
	v_add3_u32 v174, s26, v1, v158
	v_add_u32_e32 v175, s26, v156
	ds_read_b128 v[102:105], v174 offset:8192
	ds_read_b128 v[90:93], v174 offset:9216
	ds_read_b128 v[106:109], v175 offset:26624
	ds_read_b128 v[98:101], v175 offset:26688
	ds_read_b128 v[86:89], v174 offset:10240
	ds_read_b128 v[74:77], v174 offset:11264
	ds_read_b128 v[94:97], v175 offset:26752
	ds_read_b128 v[82:85], v175 offset:26816
	ds_read_b128 v[70:73], v174 offset:12288
	ds_read_b128 v[58:61], v174 offset:13312
	ds_read_b128 v[78:81], v175 offset:26880
	ds_read_b128 v[66:69], v175 offset:26944
	ds_read_b128 v[54:57], v174 offset:14336
	ds_read_b128 v[46:49], v174 offset:15360
	ds_read_b128 v[62:65], v175 offset:27008
	ds_read_b128 v[50:53], v175 offset:27072
	v_cvt_pk_bf16_f32 v170, v10, v11
	v_cvt_pk_bf16_f32 v171, v12, v13
	v_cvt_pk_bf16_f32 v172, v14, v15
	v_cvt_pk_bf16_f32 v173, v16, v17
	s_and_b64 vcc, exec, s[12:13]
	s_nop 0
	v_mfma_f32_16x16x32_bf16 v[134:137], v[170:173], v[134:137], 0
	v_mfma_f32_16x16x32_bf16 v[138:141], v[170:173], v[138:141], 0
	v_cvt_pk_bf16_f32 v170, v18, v19
	v_cvt_pk_bf16_f32 v171, v20, v21
	v_cvt_pk_bf16_f32 v172, v22, v23
	v_cvt_pk_bf16_f32 v173, v24, v25
	s_nop 0
	v_mfma_f32_16x16x32_bf16 v[126:129], v[170:173], v[126:129], v[134:137]
	v_cvt_pk_bf16_f32 v134, v26, v27
	v_cvt_pk_bf16_f32 v135, v28, v29
	v_cvt_pk_bf16_f32 v136, v30, v31
	v_mfma_f32_16x16x32_bf16 v[130:133], v[170:173], v[130:133], v[138:141]
	v_cvt_pk_bf16_f32 v137, v32, v33
	s_nop 3
	v_mfma_f32_16x16x32_bf16 v[118:121], v[134:137], v[118:121], v[126:129]
	v_cvt_pk_bf16_f32 v126, v34, v35
	v_cvt_pk_bf16_f32 v127, v36, v37
	v_cvt_pk_bf16_f32 v128, v38, v39
	v_mfma_f32_16x16x32_bf16 v[122:125], v[134:137], v[122:125], v[130:133]
	v_cvt_pk_bf16_f32 v129, v40, v41
	s_nop 0
	v_mfma_f32_16x16x32_bf16 v[114:117], v[126:129], v[114:117], v[118:121]
	v_mfma_f32_16x16x32_bf16 v[110:113], v[126:129], v[110:113], v[122:125]
	s_cbranch_vccnz .LBB0_1533
	v_mfma_f32_16x16x32_bf16 v[114:117], v[42:45], v[2:5], v[114:117]
	v_mfma_f32_16x16x32_bf16 v[110:113], v[42:45], v[6:9], v[110:113]
.LBB0_1533:
	s_add_i32 s28, s36, 4
	s_cmp_lt_u32 s35, 8
	s_cselect_b32 s26, 0x100, -8
	s_add_i32 s29, s26, s35
	s_and_b64 s[26:27], s[18:19], exec
	s_cselect_b32 s26, s29, s28
	s_lshl_b32 s26, s26, 5
	s_ashr_i32 s27, s26, 31
	v_lshl_add_u64 v[118:119], v[152:153], 0, s[26:27]
	v_mad_u64_u32 v[120:121], s[26:27], v118, s37, v[154:155]
	v_mov_b32_e32 v118, v121
	v_mad_u64_u32 v[118:119], s[26:27], v119, s37, v[118:119]
	v_mov_b32_e32 v121, v118
	v_cvt_pk_bf16_f32 v114, v114, v115
	v_cvt_pk_bf16_f32 v115, v116, v117
	global_store_dwordx2 v[120:121], v[114:115], off
	v_cvt_pk_bf16_f32 v110, v110, v111
	v_cvt_pk_bf16_f32 v111, v112, v113
	v_add_co_u32_e32 v112, vcc, 0x18000, v120
	s_nop 1
	v_addc_co_u32_e32 v113, vcc, 0, v118, vcc
	global_store_dwordx2 v[112:113], v[110:111], off
	s_waitcnt lgkmcnt(0)
	s_add_i32 s46, s35, 2
	s_and_b32 s45, 0xffff, s46
	s_mul_i32 s45, s45, 0xaaab
	s_lshr_b32 s45, s45, 18
	s_mul_i32 s45, s45, 6
	s_sub_i32 s45, s46, s45
	s_mulk_i32 s45, 0x6a00
	v_add_u32_e32 v176, s45, v157
	v_add_u32_e32 v177, v176, v167
	ds_read_b128 v[134:137], v177
	v_add_u32_e32 v178, v176, v166
	ds_read_b128 v[138:141], v177 offset:4096
	ds_read_b128 v[126:129], v178
	v_add_u32_e32 v177, v176, v168
	ds_read_b128 v[130:133], v178 offset:4096
	ds_read_b128 v[118:121], v177
	v_add_u32_e32 v176, v176, v169
	ds_read_b128 v[122:125], v177 offset:4096
	ds_read_b128 v[114:117], v176
	ds_read_b128 v[110:113], v176 offset:4096
	s_and_b64 vcc, exec, s[12:13]
	s_cbranch_vccnz .Lsc_noa
	v_add_u32_e32 v179, s45, v160
	ds_read_b128 v[2:5], v179 offset:24576
	ds_read_b128 v[6:9], v179 offset:25600
